# stack + MoBA work split weights counted in whole 256-query rounds
# speedup vs baseline: 1.0067x; 1.0002x over previous
.LBB0_303:
	s_lshl_b32 s0, s33, 3
	s_and_b32 s0, s0, 56
	s_ashr_i32 s1, s33, 5
	s_add_i32 s76, s0, s1
	s_barrier
	s_and_saveexec_b64 s[0:1], s[74:75]
	s_cbranch_execz .LBB0_305
	v_lshl_add_u32 v0, s76, 5, v170
	v_ashrrev_i32_e32 v1, 31, v0
	v_lshl_add_u64 v[0:1], v[0:1], 2, s[20:21]
	global_load_dword v0, v[0:1], off
	s_waitcnt vmcnt(0)
	v_add_u32_e32 v0, 0xff, v0
	v_and_b32_e32 v0, 0xffffff00, v0
	v_add_u32_e32 v0, 0x180, v0
	ds_write_b32 v198, v0
